# previous best + rw_scan step: dot-product ops issued back to back, every DPP gap filled with useful VALU (two s_nop fewer per step)
# speedup vs baseline: 1.0213x; 1.0068x over previous
.LBB0_774:
	s_and_b32 s11, s10, 1
	s_mul_i32 s0, s11, 0x5400
	s_add_i32 s0, s0, 16
	v_lshl_add_u32 v126, v87, 2, s0
	v_add3_u32 v124, s0, v91, v92
	s_lshl_b32 s0, s11, 10
	s_add_i32 s0, s0, 0xe810
	v_add_u32_e32 v127, v91, v92
	v_lshl_add_u32 v127, v127, 4, s0
	ds_read_b128 v[136:139], v127 offset:0
	ds_read_b128 v[184:187], v126 offset:0
	ds_read_b128 v[196:199], v126 offset:768
	ds_read_b128 v[188:191], v126 offset:256
	ds_read_b128 v[200:203], v126 offset:1024
	ds_read_b128 v[192:195], v126 offset:512
	ds_read_b128 v[206:209], v126 offset:1344
	ds_read_b128 v[218:221], v126 offset:2112
	ds_read_b128 v[210:213], v126 offset:1600
	ds_read_b128 v[222:225], v126 offset:2368
	ds_read_b128 v[214:217], v126 offset:1856
	s_waitcnt lgkmcnt(5)
	v_pk_mul_f32 v[250:251], v[8:9], v[184:185]
	v_pk_fma_f32 v[250:251], v[10:11], v[186:187], v[250:251]
	v_add_f32_e32 v14, v250, v251
	v_pk_mul_f32 v[252:253], v[136:137], v[196:197] op_sel_hi:[0,1]
	v_pk_mul_f32 v[254:255], v[136:137], v[198:199] op_sel_hi:[0,1]
	v_add_f32_dpp v14, v14, v14 quad_perm:[1,0,3,2] row_mask:0xf bank_mask:0xf bound_ctrl:1
	v_pk_fma_f32 v[252:253], v[8:9], v[188:189], v[252:253]
	v_pk_fma_f32 v[254:255], v[10:11], v[190:191], v[254:255]
	v_add_f32_dpp v14, v14, v14 quad_perm:[2,3,0,1] row_mask:0xf bank_mask:0xf bound_ctrl:1
	ds_read_b128 v[228:231], v126 offset:2688
	ds_read_b128 v[240:243], v126 offset:3456
	v_add_f32_dpp v14, v14, v14 row_half_mirror row_mask:0xf bank_mask:0xf bound_ctrl:1
	ds_read_b128 v[232:235], v126 offset:2944
	ds_read_b128 v[244:247], v126 offset:3712
	v_add_f32_dpp v14, v14, v14 row_mirror row_mask:0xf bank_mask:0xf bound_ctrl:1
	v_pk_fma_f32 v[10:11], v[14:15], v[194:195], v[254:255] op_sel_hi:[0,1,1]
	v_pk_fma_f32 v[8:9], v[14:15], v[192:193], v[252:253] op_sel_hi:[0,1,1]
	ds_read_b128 v[236:239], v126 offset:3200
	s_waitcnt lgkmcnt(5)
	v_pk_mul_f32 v[250:251], v[8:9], v[206:207]
	v_pk_fma_f32 v[250:251], v[10:11], v[208:209], v[250:251]
	v_add_f32_e32 v14, v250, v251
	v_pk_mul_f32 v[252:253], v[136:137], v[218:219] op_sel:[1,0] op_sel_hi:[1,1]
	v_pk_mul_f32 v[254:255], v[136:137], v[220:221] op_sel:[1,0] op_sel_hi:[1,1]
	v_add_f32_dpp v14, v14, v14 quad_perm:[1,0,3,2] row_mask:0xf bank_mask:0xf bound_ctrl:1
	v_pk_fma_f32 v[252:253], v[8:9], v[210:211], v[252:253]
	v_pk_fma_f32 v[254:255], v[10:11], v[212:213], v[254:255]
	v_add_f32_dpp v14, v14, v14 quad_perm:[2,3,0,1] row_mask:0xf bank_mask:0xf bound_ctrl:1
	v_pk_mul_f32 v[12:13], v[8:9], v[200:201]
	v_pk_fma_f32 v[12:13], v[10:11], v[202:203], v[12:13]
	v_add_f32_dpp v14, v14, v14 row_half_mirror row_mask:0xf bank_mask:0xf bound_ctrl:1
	v_add_f32_e32 v18, v12, v13
	s_nop 0
	v_add_f32_dpp v14, v14, v14 row_mirror row_mask:0xf bank_mask:0xf bound_ctrl:1
	v_pk_fma_f32 v[10:11], v[14:15], v[216:217], v[254:255] op_sel_hi:[0,1,1]
	v_pk_fma_f32 v[8:9], v[14:15], v[214:215], v[252:253] op_sel_hi:[0,1,1]
	ds_read_b128 v[184:187], v126 offset:4032
	ds_read_b128 v[196:199], v126 offset:4800
	ds_read_b128 v[188:191], v126 offset:4288
	ds_read_b128 v[200:203], v126 offset:5056
	ds_read_b128 v[192:195], v126 offset:4544
	s_waitcnt lgkmcnt(5)
	v_pk_mul_f32 v[250:251], v[8:9], v[228:229]
	v_pk_fma_f32 v[250:251], v[10:11], v[230:231], v[250:251]
	v_add_f32_e32 v14, v250, v251
	v_pk_mul_f32 v[252:253], v[138:139], v[240:241] op_sel_hi:[0,1]
	v_pk_mul_f32 v[254:255], v[138:139], v[242:243] op_sel_hi:[0,1]
	v_add_f32_dpp v14, v14, v14 quad_perm:[1,0,3,2] row_mask:0xf bank_mask:0xf bound_ctrl:1
	v_pk_fma_f32 v[252:253], v[8:9], v[232:233], v[252:253]
	v_pk_fma_f32 v[254:255], v[10:11], v[234:235], v[254:255]
	v_add_f32_dpp v14, v14, v14 quad_perm:[2,3,0,1] row_mask:0xf bank_mask:0xf bound_ctrl:1
	v_pk_mul_f32 v[12:13], v[8:9], v[222:223]
	v_pk_fma_f32 v[12:13], v[10:11], v[224:225], v[12:13]
	v_add_f32_dpp v14, v14, v14 row_half_mirror row_mask:0xf bank_mask:0xf bound_ctrl:1
	v_add_f32_e32 v19, v12, v13
	s_nop 0
	v_add_f32_dpp v14, v14, v14 row_mirror row_mask:0xf bank_mask:0xf bound_ctrl:1
	v_pk_fma_f32 v[10:11], v[14:15], v[238:239], v[254:255] op_sel_hi:[0,1,1]
	v_pk_fma_f32 v[8:9], v[14:15], v[236:237], v[252:253] op_sel_hi:[0,1,1]
	ds_read_b128 v[140:143], v127 offset:16
	ds_read_b128 v[206:209], v126 offset:5376
	ds_read_b128 v[218:221], v126 offset:6144
	ds_read_b128 v[210:213], v126 offset:5632
	ds_read_b128 v[222:225], v126 offset:6400
	ds_read_b128 v[214:217], v126 offset:5888
	s_waitcnt lgkmcnt(6)
	v_pk_mul_f32 v[250:251], v[8:9], v[184:185]
	v_pk_fma_f32 v[250:251], v[10:11], v[186:187], v[250:251]
	v_add_f32_e32 v14, v250, v251
	v_pk_mul_f32 v[252:253], v[138:139], v[196:197] op_sel:[1,0] op_sel_hi:[1,1]
	v_pk_mul_f32 v[254:255], v[138:139], v[198:199] op_sel:[1,0] op_sel_hi:[1,1]
	v_add_f32_dpp v14, v14, v14 quad_perm:[1,0,3,2] row_mask:0xf bank_mask:0xf bound_ctrl:1
	v_pk_fma_f32 v[252:253], v[8:9], v[188:189], v[252:253]
	v_pk_fma_f32 v[254:255], v[10:11], v[190:191], v[254:255]
	v_add_f32_dpp v14, v14, v14 quad_perm:[2,3,0,1] row_mask:0xf bank_mask:0xf bound_ctrl:1
	v_pk_mul_f32 v[12:13], v[8:9], v[244:245]
	v_pk_fma_f32 v[12:13], v[10:11], v[246:247], v[12:13]
	v_add_f32_dpp v14, v14, v14 row_half_mirror row_mask:0xf bank_mask:0xf bound_ctrl:1
	v_add_f32_e32 v20, v12, v13
	s_nop 0
	v_add_f32_dpp v14, v14, v14 row_mirror row_mask:0xf bank_mask:0xf bound_ctrl:1
	v_pk_fma_f32 v[10:11], v[14:15], v[194:195], v[254:255] op_sel_hi:[0,1,1]
	v_pk_fma_f32 v[8:9], v[14:15], v[192:193], v[252:253] op_sel_hi:[0,1,1]
	ds_read_b128 v[228:231], v126 offset:6720
	ds_read_b128 v[240:243], v126 offset:7488
	ds_read_b128 v[232:235], v126 offset:6976
	ds_read_b128 v[244:247], v126 offset:7744
	ds_read_b128 v[236:239], v126 offset:7232
	s_waitcnt lgkmcnt(5)
	v_pk_mul_f32 v[250:251], v[8:9], v[206:207]
	v_pk_fma_f32 v[250:251], v[10:11], v[208:209], v[250:251]
	v_add_f32_e32 v14, v250, v251
	v_pk_mul_f32 v[252:253], v[140:141], v[218:219] op_sel_hi:[0,1]
	v_pk_mul_f32 v[254:255], v[140:141], v[220:221] op_sel_hi:[0,1]
	v_add_f32_dpp v14, v14, v14 quad_perm:[1,0,3,2] row_mask:0xf bank_mask:0xf bound_ctrl:1
	v_pk_fma_f32 v[252:253], v[8:9], v[210:211], v[252:253]
	v_pk_fma_f32 v[254:255], v[10:11], v[212:213], v[254:255]
	v_add_f32_dpp v14, v14, v14 quad_perm:[2,3,0,1] row_mask:0xf bank_mask:0xf bound_ctrl:1
	v_pk_mul_f32 v[12:13], v[8:9], v[200:201]
	v_pk_fma_f32 v[12:13], v[10:11], v[202:203], v[12:13]
	v_add_f32_dpp v14, v14, v14 row_half_mirror row_mask:0xf bank_mask:0xf bound_ctrl:1
	v_add_f32_e32 v21, v12, v13
	s_nop 0
	v_add_f32_dpp v14, v14, v14 row_mirror row_mask:0xf bank_mask:0xf bound_ctrl:1
	v_pk_fma_f32 v[10:11], v[14:15], v[216:217], v[254:255] op_sel_hi:[0,1,1]
	v_pk_fma_f32 v[8:9], v[14:15], v[214:215], v[252:253] op_sel_hi:[0,1,1]
	ds_read_b128 v[184:187], v126 offset:8064
	ds_read_b128 v[196:199], v126 offset:8832
	ds_read_b128 v[188:191], v126 offset:8320
	ds_read_b128 v[200:203], v126 offset:9088
	ds_read_b128 v[192:195], v126 offset:8576
	s_waitcnt lgkmcnt(5)
	v_pk_mul_f32 v[250:251], v[8:9], v[228:229]
	v_pk_fma_f32 v[250:251], v[10:11], v[230:231], v[250:251]
	v_add_f32_e32 v14, v250, v251
	v_pk_mul_f32 v[252:253], v[140:141], v[240:241] op_sel:[1,0] op_sel_hi:[1,1]
	v_pk_mul_f32 v[254:255], v[140:141], v[242:243] op_sel:[1,0] op_sel_hi:[1,1]
	v_add_f32_dpp v14, v14, v14 quad_perm:[1,0,3,2] row_mask:0xf bank_mask:0xf bound_ctrl:1
	v_pk_fma_f32 v[252:253], v[8:9], v[232:233], v[252:253]
	v_pk_fma_f32 v[254:255], v[10:11], v[234:235], v[254:255]
	v_add_f32_dpp v14, v14, v14 quad_perm:[2,3,0,1] row_mask:0xf bank_mask:0xf bound_ctrl:1
	v_pk_mul_f32 v[12:13], v[8:9], v[222:223]
	v_pk_fma_f32 v[12:13], v[10:11], v[224:225], v[12:13]
	v_add_f32_dpp v14, v14, v14 row_half_mirror row_mask:0xf bank_mask:0xf bound_ctrl:1
	v_add_f32_e32 v22, v12, v13
	s_nop 0
	v_add_f32_dpp v14, v14, v14 row_mirror row_mask:0xf bank_mask:0xf bound_ctrl:1
	v_pk_fma_f32 v[10:11], v[14:15], v[238:239], v[254:255] op_sel_hi:[0,1,1]
	v_pk_fma_f32 v[8:9], v[14:15], v[236:237], v[252:253] op_sel_hi:[0,1,1]
	ds_read_b128 v[206:209], v126 offset:9408
	ds_read_b128 v[218:221], v126 offset:10176
	ds_read_b128 v[210:213], v126 offset:9664
	ds_read_b128 v[222:225], v126 offset:10432
	ds_read_b128 v[214:217], v126 offset:9920
	s_waitcnt lgkmcnt(5)
	v_pk_mul_f32 v[250:251], v[8:9], v[184:185]
	v_pk_fma_f32 v[250:251], v[10:11], v[186:187], v[250:251]
	v_add_f32_e32 v14, v250, v251
	v_pk_mul_f32 v[252:253], v[142:143], v[196:197] op_sel_hi:[0,1]
	v_pk_mul_f32 v[254:255], v[142:143], v[198:199] op_sel_hi:[0,1]
	v_add_f32_dpp v14, v14, v14 quad_perm:[1,0,3,2] row_mask:0xf bank_mask:0xf bound_ctrl:1
	v_pk_fma_f32 v[252:253], v[8:9], v[188:189], v[252:253]
	v_pk_fma_f32 v[254:255], v[10:11], v[190:191], v[254:255]
	v_add_f32_dpp v14, v14, v14 quad_perm:[2,3,0,1] row_mask:0xf bank_mask:0xf bound_ctrl:1
	v_pk_mul_f32 v[12:13], v[8:9], v[244:245]
	v_pk_fma_f32 v[12:13], v[10:11], v[246:247], v[12:13]
	v_add_f32_dpp v14, v14, v14 row_half_mirror row_mask:0xf bank_mask:0xf bound_ctrl:1
	v_add_f32_e32 v23, v12, v13
	s_nop 0
	v_add_f32_dpp v14, v14, v14 row_mirror row_mask:0xf bank_mask:0xf bound_ctrl:1
	v_pk_fma_f32 v[10:11], v[14:15], v[194:195], v[254:255] op_sel_hi:[0,1,1]
	v_pk_fma_f32 v[8:9], v[14:15], v[192:193], v[252:253] op_sel_hi:[0,1,1]
	ds_read_b128 v[136:139], v127 offset:32
	ds_read_b128 v[228:231], v126 offset:10752
	ds_read_b128 v[240:243], v126 offset:11520
	ds_read_b128 v[232:235], v126 offset:11008
	ds_read_b128 v[244:247], v126 offset:11776
	ds_read_b128 v[236:239], v126 offset:11264
	s_waitcnt lgkmcnt(6)
	v_pk_mul_f32 v[250:251], v[8:9], v[206:207]
	v_pk_fma_f32 v[250:251], v[10:11], v[208:209], v[250:251]
	v_add_f32_e32 v14, v250, v251
	v_pk_mul_f32 v[252:253], v[142:143], v[218:219] op_sel:[1,0] op_sel_hi:[1,1]
	v_pk_mul_f32 v[254:255], v[142:143], v[220:221] op_sel:[1,0] op_sel_hi:[1,1]
	v_add_f32_dpp v14, v14, v14 quad_perm:[1,0,3,2] row_mask:0xf bank_mask:0xf bound_ctrl:1
	v_pk_fma_f32 v[252:253], v[8:9], v[210:211], v[252:253]
	v_pk_fma_f32 v[254:255], v[10:11], v[212:213], v[254:255]
	v_add_f32_dpp v14, v14, v14 quad_perm:[2,3,0,1] row_mask:0xf bank_mask:0xf bound_ctrl:1
	v_pk_mul_f32 v[12:13], v[8:9], v[200:201]
	v_pk_fma_f32 v[12:13], v[10:11], v[202:203], v[12:13]
	v_add_f32_dpp v14, v14, v14 row_half_mirror row_mask:0xf bank_mask:0xf bound_ctrl:1
	v_add_f32_e32 v24, v12, v13
	s_nop 0
	v_add_f32_dpp v14, v14, v14 row_mirror row_mask:0xf bank_mask:0xf bound_ctrl:1
	v_pk_fma_f32 v[10:11], v[14:15], v[216:217], v[254:255] op_sel_hi:[0,1,1]
	v_pk_fma_f32 v[8:9], v[14:15], v[214:215], v[252:253] op_sel_hi:[0,1,1]
	ds_read_b128 v[184:187], v126 offset:12096
	ds_read_b128 v[196:199], v126 offset:12864
	ds_read_b128 v[188:191], v126 offset:12352
	ds_read_b128 v[200:203], v126 offset:13120
	ds_read_b128 v[192:195], v126 offset:12608
	s_waitcnt lgkmcnt(5)
	v_pk_mul_f32 v[250:251], v[8:9], v[228:229]
	v_pk_fma_f32 v[250:251], v[10:11], v[230:231], v[250:251]
	v_add_f32_e32 v14, v250, v251
	v_pk_mul_f32 v[252:253], v[136:137], v[240:241] op_sel_hi:[0,1]
	v_pk_mul_f32 v[254:255], v[136:137], v[242:243] op_sel_hi:[0,1]
	v_add_f32_dpp v14, v14, v14 quad_perm:[1,0,3,2] row_mask:0xf bank_mask:0xf bound_ctrl:1
	v_pk_fma_f32 v[252:253], v[8:9], v[232:233], v[252:253]
	v_pk_fma_f32 v[254:255], v[10:11], v[234:235], v[254:255]
	v_add_f32_dpp v14, v14, v14 quad_perm:[2,3,0,1] row_mask:0xf bank_mask:0xf bound_ctrl:1
	v_pk_mul_f32 v[12:13], v[8:9], v[222:223]
	v_pk_fma_f32 v[12:13], v[10:11], v[224:225], v[12:13]
	v_add_f32_dpp v14, v14, v14 row_half_mirror row_mask:0xf bank_mask:0xf bound_ctrl:1
	v_add_f32_e32 v25, v12, v13
	s_nop 0
	v_add_f32_dpp v14, v14, v14 row_mirror row_mask:0xf bank_mask:0xf bound_ctrl:1
	v_pk_fma_f32 v[10:11], v[14:15], v[238:239], v[254:255] op_sel_hi:[0,1,1]
	v_pk_fma_f32 v[8:9], v[14:15], v[236:237], v[252:253] op_sel_hi:[0,1,1]
	ds_read_b128 v[206:209], v126 offset:13440
	ds_read_b128 v[218:221], v126 offset:14208
	ds_read_b128 v[210:213], v126 offset:13696
	ds_read_b128 v[222:225], v126 offset:14464
	ds_read_b128 v[214:217], v126 offset:13952
	s_waitcnt vmcnt(0)
	s_xor_b32 s0, s11, 1
	v_lshl_add_u32 v170, s0, 10, v130
	s_mulk_i32 s0, 0x5400
	v_add_u32_e32 v82, s0, v79
	v_lshlrev_b32_e32 v34, 16, v74
	v_and_b32_e32 v35, 0xffff0000, v74
	v_lshlrev_b32_e32 v36, 16, v75
	v_and_b32_e32 v37, 0xffff0000, v75
	v_lshl_add_u32 v83, v50, 2, v82
	v_pk_mul_f32 v[38:39], v[0:1], v[34:35]
	v_pk_mul_f32 v[40:41], v[2:3], v[36:37]
	v_lshlrev_b32_e32 v120, 16, v72
	v_pk_mul_f32 v[42:43], v[78:79], v[38:39] op_sel_hi:[0,1] neg_lo:[1,0] neg_hi:[1,0]
	v_pk_mul_f32 v[44:45], v[78:79], v[40:41] op_sel_hi:[0,1] neg_lo:[1,0] neg_hi:[1,0]
	v_and_b32_e32 v121, 0xffff0000, v72
	v_lshlrev_b32_e32 v122, 16, v73
	v_and_b32_e32 v123, 0xffff0000, v73
	ds_write_b128 v83, v[42:45]
	v_lshlrev_b32_e32 v38, 16, v76
	v_and_b32_e32 v39, 0xffff0000, v76
	v_lshlrev_b32_e32 v40, 16, v77
	v_and_b32_e32 v41, 0xffff0000, v77
	v_pk_add_f32 v[38:39], v[38:39], 1.0 op_sel_hi:[1,0] neg_lo:[1,0] neg_hi:[1,0]
	v_pk_add_f32 v[40:41], v[40:41], 1.0 op_sel_hi:[1,0] neg_lo:[1,0] neg_hi:[1,0]
	v_lshl_add_u32 v85, v48, 2, v82
	ds_write_b128 v83, v[38:41] offset:256
	v_pk_mul_f32 v[38:39], v[42:43], v[120:121] neg_lo:[1,0] neg_hi:[1,0]
	v_pk_mul_f32 v[40:41], v[44:45], v[122:123] neg_lo:[1,0] neg_hi:[1,0]
	v_pk_add_f32 v[120:121], v[120:121], -1.0 op_sel_hi:[1,0]
	v_pk_add_f32 v[122:123], v[122:123], -1.0 op_sel_hi:[1,0]
	ds_write_b128 v83, v[38:41] offset:512
	v_pk_fma_f32 v[120:121], v[4:5], v[120:121], 1.0 op_sel_hi:[1,1,0]
	v_pk_fma_f32 v[122:123], v[6:7], v[122:123], 1.0 op_sel_hi:[1,1,0]
	v_lshlrev_b32_e32 v42, 16, v62
	v_and_b32_e32 v43, 0xffff0000, v62
	v_pk_mul_f32 v[120:121], v[120:121], v[34:35]
	v_pk_mul_f32 v[122:123], v[122:123], v[36:37]
	v_lshlrev_b32_e32 v44, 16, v63
	v_and_b32_e32 v45, 0xffff0000, v63
	v_lshlrev_b32_e32 v84, 16, v102
	ds_write_b128 v83, v[120:123] offset:768
	ds_write_b128 v83, v[42:45] offset:1024
	ds_write_b32 v85, v84 offset:1280
	ds_write_b32 v170, v84
	s_cmpk_eq_i32 s6, 0x20e0
	s_cbranch_scc1 .Lscan_pf_skip
	v_add_u32_e32 v131, v132, v131
	s_cmp_eq_u32 s10, 14
	s_cbranch_scc0 .Lscan_pf_nox
	v_mov_b32_e32 v131, v133

.Lscan_pf_skip:
	s_waitcnt lgkmcnt(12)
	v_pk_mul_f32 v[250:251], v[8:9], v[184:185]
	v_pk_fma_f32 v[250:251], v[10:11], v[186:187], v[250:251]
	v_add_f32_e32 v14, v250, v251
	v_pk_mul_f32 v[252:253], v[136:137], v[196:197] op_sel:[1,0] op_sel_hi:[1,1]
	v_pk_mul_f32 v[254:255], v[136:137], v[198:199] op_sel:[1,0] op_sel_hi:[1,1]
	v_add_f32_dpp v14, v14, v14 quad_perm:[1,0,3,2] row_mask:0xf bank_mask:0xf bound_ctrl:1
	v_pk_fma_f32 v[252:253], v[8:9], v[188:189], v[252:253]
	v_pk_fma_f32 v[254:255], v[10:11], v[190:191], v[254:255]
	v_add_f32_dpp v14, v14, v14 quad_perm:[2,3,0,1] row_mask:0xf bank_mask:0xf bound_ctrl:1
	v_pk_mul_f32 v[12:13], v[8:9], v[244:245]
	v_pk_fma_f32 v[12:13], v[10:11], v[246:247], v[12:13]
	v_add_f32_dpp v14, v14, v14 row_half_mirror row_mask:0xf bank_mask:0xf bound_ctrl:1
	v_add_f32_e32 v26, v12, v13
	s_nop 0
	v_add_f32_dpp v14, v14, v14 row_mirror row_mask:0xf bank_mask:0xf bound_ctrl:1
	v_pk_fma_f32 v[10:11], v[14:15], v[194:195], v[254:255] op_sel_hi:[0,1,1]
	v_pk_fma_f32 v[8:9], v[14:15], v[192:193], v[252:253] op_sel_hi:[0,1,1]
	ds_read_b128 v[228:231], v126 offset:14784
	ds_read_b128 v[240:243], v126 offset:15552
	ds_read_b128 v[232:235], v126 offset:15040
	ds_read_b128 v[244:247], v126 offset:15808
	ds_read_b128 v[236:239], v126 offset:15296
	s_waitcnt lgkmcnt(12)
	v_pk_mul_f32 v[250:251], v[8:9], v[206:207]
	v_pk_fma_f32 v[250:251], v[10:11], v[208:209], v[250:251]
	v_add_f32_e32 v14, v250, v251
	v_pk_mul_f32 v[252:253], v[138:139], v[218:219] op_sel_hi:[0,1]
	v_pk_mul_f32 v[254:255], v[138:139], v[220:221] op_sel_hi:[0,1]
	v_add_f32_dpp v14, v14, v14 quad_perm:[1,0,3,2] row_mask:0xf bank_mask:0xf bound_ctrl:1
	v_pk_fma_f32 v[252:253], v[8:9], v[210:211], v[252:253]
	v_pk_fma_f32 v[254:255], v[10:11], v[212:213], v[254:255]
	v_add_f32_dpp v14, v14, v14 quad_perm:[2,3,0,1] row_mask:0xf bank_mask:0xf bound_ctrl:1
	v_pk_mul_f32 v[12:13], v[8:9], v[200:201]
	v_pk_fma_f32 v[12:13], v[10:11], v[202:203], v[12:13]
	v_add_f32_dpp v14, v14, v14 row_half_mirror row_mask:0xf bank_mask:0xf bound_ctrl:1
	v_add_f32_e32 v27, v12, v13
	s_nop 0
	v_add_f32_dpp v14, v14, v14 row_mirror row_mask:0xf bank_mask:0xf bound_ctrl:1
	v_pk_fma_f32 v[10:11], v[14:15], v[216:217], v[254:255] op_sel_hi:[0,1,1]
	v_pk_fma_f32 v[8:9], v[14:15], v[214:215], v[252:253] op_sel_hi:[0,1,1]
	ds_read_b128 v[140:143], v127 offset:48
	ds_read_b128 v[184:187], v126 offset:16128
	ds_read_b128 v[196:199], v126 offset:16896
	ds_read_b128 v[188:191], v126 offset:16384
	ds_read_b128 v[200:203], v126 offset:17152
	ds_read_b128 v[192:195], v126 offset:16640
	s_waitcnt lgkmcnt(6)
	v_pk_mul_f32 v[250:251], v[8:9], v[228:229]
	v_pk_fma_f32 v[250:251], v[10:11], v[230:231], v[250:251]
	v_add_f32_e32 v14, v250, v251
	v_pk_mul_f32 v[252:253], v[138:139], v[240:241] op_sel:[1,0] op_sel_hi:[1,1]
	v_pk_mul_f32 v[254:255], v[138:139], v[242:243] op_sel:[1,0] op_sel_hi:[1,1]
	v_add_f32_dpp v14, v14, v14 quad_perm:[1,0,3,2] row_mask:0xf bank_mask:0xf bound_ctrl:1
	v_pk_fma_f32 v[252:253], v[8:9], v[232:233], v[252:253]
	v_pk_fma_f32 v[254:255], v[10:11], v[234:235], v[254:255]
	v_add_f32_dpp v14, v14, v14 quad_perm:[2,3,0,1] row_mask:0xf bank_mask:0xf bound_ctrl:1
	v_pk_mul_f32 v[12:13], v[8:9], v[222:223]
	v_pk_fma_f32 v[12:13], v[10:11], v[224:225], v[12:13]
	v_add_f32_dpp v14, v14, v14 row_half_mirror row_mask:0xf bank_mask:0xf bound_ctrl:1
	v_add_f32_e32 v28, v12, v13
	s_nop 0
	v_add_f32_dpp v14, v14, v14 row_mirror row_mask:0xf bank_mask:0xf bound_ctrl:1
	v_pk_fma_f32 v[10:11], v[14:15], v[238:239], v[254:255] op_sel_hi:[0,1,1]
	v_pk_fma_f32 v[8:9], v[14:15], v[236:237], v[252:253] op_sel_hi:[0,1,1]
	ds_read_b128 v[206:209], v126 offset:17472
	ds_read_b128 v[218:221], v126 offset:18240
	ds_read_b128 v[210:213], v126 offset:17728
	ds_read_b128 v[222:225], v126 offset:18496
	ds_read_b128 v[214:217], v126 offset:17984
	s_waitcnt lgkmcnt(5)
	v_pk_mul_f32 v[250:251], v[8:9], v[184:185]
	v_pk_fma_f32 v[250:251], v[10:11], v[186:187], v[250:251]
	v_add_f32_e32 v14, v250, v251
	v_pk_mul_f32 v[252:253], v[140:141], v[196:197] op_sel_hi:[0,1]
	v_pk_mul_f32 v[254:255], v[140:141], v[198:199] op_sel_hi:[0,1]
	v_add_f32_dpp v14, v14, v14 quad_perm:[1,0,3,2] row_mask:0xf bank_mask:0xf bound_ctrl:1
	v_pk_fma_f32 v[252:253], v[8:9], v[188:189], v[252:253]
	v_pk_fma_f32 v[254:255], v[10:11], v[190:191], v[254:255]
	v_add_f32_dpp v14, v14, v14 quad_perm:[2,3,0,1] row_mask:0xf bank_mask:0xf bound_ctrl:1
	v_pk_mul_f32 v[12:13], v[8:9], v[244:245]
	v_pk_fma_f32 v[12:13], v[10:11], v[246:247], v[12:13]
	v_add_f32_dpp v14, v14, v14 row_half_mirror row_mask:0xf bank_mask:0xf bound_ctrl:1
	v_add_f32_e32 v29, v12, v13
	s_nop 0
	v_add_f32_dpp v14, v14, v14 row_mirror row_mask:0xf bank_mask:0xf bound_ctrl:1
	v_pk_fma_f32 v[10:11], v[14:15], v[194:195], v[254:255] op_sel_hi:[0,1,1]
	v_pk_fma_f32 v[8:9], v[14:15], v[192:193], v[252:253] op_sel_hi:[0,1,1]
	ds_read_b128 v[228:231], v126 offset:18816
	ds_read_b128 v[240:243], v126 offset:19584
	ds_read_b128 v[232:235], v126 offset:19072
	ds_read_b128 v[244:247], v126 offset:19840
	ds_read_b128 v[236:239], v126 offset:19328
	s_waitcnt lgkmcnt(5)
	v_pk_mul_f32 v[250:251], v[8:9], v[206:207]
	v_pk_fma_f32 v[250:251], v[10:11], v[208:209], v[250:251]
	v_add_f32_e32 v14, v250, v251
	v_pk_mul_f32 v[252:253], v[140:141], v[218:219] op_sel:[1,0] op_sel_hi:[1,1]
	v_pk_mul_f32 v[254:255], v[140:141], v[220:221] op_sel:[1,0] op_sel_hi:[1,1]
	v_add_f32_dpp v14, v14, v14 quad_perm:[1,0,3,2] row_mask:0xf bank_mask:0xf bound_ctrl:1
	v_pk_fma_f32 v[252:253], v[8:9], v[210:211], v[252:253]
	v_pk_fma_f32 v[254:255], v[10:11], v[212:213], v[254:255]
	v_add_f32_dpp v14, v14, v14 quad_perm:[2,3,0,1] row_mask:0xf bank_mask:0xf bound_ctrl:1
	v_pk_mul_f32 v[12:13], v[8:9], v[200:201]
	v_pk_fma_f32 v[12:13], v[10:11], v[202:203], v[12:13]
	v_add_f32_dpp v14, v14, v14 row_half_mirror row_mask:0xf bank_mask:0xf bound_ctrl:1
	v_add_f32_e32 v30, v12, v13
	s_nop 0
	v_add_f32_dpp v14, v14, v14 row_mirror row_mask:0xf bank_mask:0xf bound_ctrl:1
	v_pk_fma_f32 v[10:11], v[14:15], v[216:217], v[254:255] op_sel_hi:[0,1,1]
	v_pk_fma_f32 v[8:9], v[14:15], v[214:215], v[252:253] op_sel_hi:[0,1,1]
	ds_read_b128 v[184:187], v126 offset:20160
	ds_read_b128 v[196:199], v126 offset:20928
	ds_read_b128 v[188:191], v126 offset:20416
	ds_read_b128 v[200:203], v126 offset:21184
	ds_read_b128 v[192:195], v126 offset:20672
	s_waitcnt lgkmcnt(5)
	v_pk_mul_f32 v[250:251], v[8:9], v[228:229]
	v_pk_fma_f32 v[250:251], v[10:11], v[230:231], v[250:251]
	v_add_f32_e32 v14, v250, v251
	v_pk_mul_f32 v[252:253], v[142:143], v[240:241] op_sel_hi:[0,1]
	v_pk_mul_f32 v[254:255], v[142:143], v[242:243] op_sel_hi:[0,1]
	v_add_f32_dpp v14, v14, v14 quad_perm:[1,0,3,2] row_mask:0xf bank_mask:0xf bound_ctrl:1
	v_pk_fma_f32 v[252:253], v[8:9], v[232:233], v[252:253]
	v_pk_fma_f32 v[254:255], v[10:11], v[234:235], v[254:255]
	v_add_f32_dpp v14, v14, v14 quad_perm:[2,3,0,1] row_mask:0xf bank_mask:0xf bound_ctrl:1
	v_pk_mul_f32 v[12:13], v[8:9], v[222:223]
	v_pk_fma_f32 v[12:13], v[10:11], v[224:225], v[12:13]
	v_add_f32_dpp v14, v14, v14 row_half_mirror row_mask:0xf bank_mask:0xf bound_ctrl:1
	v_add_f32_e32 v31, v12, v13
	s_nop 0
	v_add_f32_dpp v14, v14, v14 row_mirror row_mask:0xf bank_mask:0xf bound_ctrl:1
	v_pk_fma_f32 v[10:11], v[14:15], v[238:239], v[254:255] op_sel_hi:[0,1,1]
	v_pk_fma_f32 v[8:9], v[14:15], v[236:237], v[252:253] op_sel_hi:[0,1,1]
	s_waitcnt lgkmcnt(0)
	v_pk_mul_f32 v[250:251], v[8:9], v[184:185]
	v_pk_fma_f32 v[250:251], v[10:11], v[186:187], v[250:251]
	v_add_f32_e32 v14, v250, v251
	v_pk_mul_f32 v[252:253], v[142:143], v[196:197] op_sel:[1,0] op_sel_hi:[1,1]
	v_pk_mul_f32 v[254:255], v[142:143], v[198:199] op_sel:[1,0] op_sel_hi:[1,1]
	v_add_f32_dpp v14, v14, v14 quad_perm:[1,0,3,2] row_mask:0xf bank_mask:0xf bound_ctrl:1
	v_pk_fma_f32 v[252:253], v[8:9], v[188:189], v[252:253]
	v_pk_fma_f32 v[254:255], v[10:11], v[190:191], v[254:255]
	v_add_f32_dpp v14, v14, v14 quad_perm:[2,3,0,1] row_mask:0xf bank_mask:0xf bound_ctrl:1
	v_pk_mul_f32 v[12:13], v[8:9], v[244:245]
	v_pk_fma_f32 v[12:13], v[10:11], v[246:247], v[12:13]
	v_add_f32_dpp v14, v14, v14 row_half_mirror row_mask:0xf bank_mask:0xf bound_ctrl:1
	v_add_f32_e32 v32, v12, v13
	s_nop 0
	v_add_f32_dpp v14, v14, v14 row_mirror row_mask:0xf bank_mask:0xf bound_ctrl:1
	v_pk_fma_f32 v[10:11], v[14:15], v[194:195], v[254:255] op_sel_hi:[0,1,1]
	v_pk_fma_f32 v[8:9], v[14:15], v[192:193], v[252:253] op_sel_hi:[0,1,1]
	v_pk_mul_f32 v[12:13], v[8:9], v[200:201]
	v_add_f32_dpp v34, v18, v18 row_mirror row_mask:0xf bank_mask:0x3 bound_ctrl:1
	v_pk_fma_f32 v[12:13], v[10:11], v[202:203], v[12:13]
	v_add_f32_dpp v35, v19, v19 row_mirror row_mask:0xf bank_mask:0x3 bound_ctrl:1
	v_add_f32_dpp v36, v20, v20 row_mirror row_mask:0xf bank_mask:0x3 bound_ctrl:1
	v_add_f32_e32 v33, v12, v13
	v_add_f32_dpp v37, v21, v21 row_mirror row_mask:0xf bank_mask:0x3 bound_ctrl:1
	v_add_f32_dpp v38, v22, v22 row_mirror row_mask:0xf bank_mask:0x3 bound_ctrl:1
	v_add_f32_dpp v39, v23, v23 row_mirror row_mask:0xf bank_mask:0x3 bound_ctrl:1
	v_add_f32_dpp v40, v24, v24 row_mirror row_mask:0xf bank_mask:0x3 bound_ctrl:1
	v_add_f32_dpp v41, v25, v25 row_mirror row_mask:0xf bank_mask:0x3 bound_ctrl:1
	v_add_f32_dpp v34, v26, v26 row_mirror row_mask:0xf bank_mask:0xc bound_ctrl:1
	v_add_f32_dpp v35, v27, v27 row_mirror row_mask:0xf bank_mask:0xc bound_ctrl:1
	v_add_f32_dpp v36, v28, v28 row_mirror row_mask:0xf bank_mask:0xc bound_ctrl:1
	v_add_f32_dpp v37, v29, v29 row_mirror row_mask:0xf bank_mask:0xc bound_ctrl:1
	v_add_f32_dpp v38, v30, v30 row_mirror row_mask:0xf bank_mask:0xc bound_ctrl:1
	v_add_f32_dpp v39, v31, v31 row_mirror row_mask:0xf bank_mask:0xc bound_ctrl:1
	v_add_f32_dpp v40, v32, v32 row_mirror row_mask:0xf bank_mask:0xc bound_ctrl:1
	v_add_f32_dpp v41, v33, v33 row_mirror row_mask:0xf bank_mask:0xc bound_ctrl:1
	v_add_f32_dpp v42, v34, v34 row_half_mirror row_mask:0xf bank_mask:0x5 bound_ctrl:1
	v_add_f32_dpp v43, v35, v35 row_half_mirror row_mask:0xf bank_mask:0x5 bound_ctrl:1
	v_add_f32_dpp v44, v36, v36 row_half_mirror row_mask:0xf bank_mask:0x5 bound_ctrl:1
	v_add_f32_dpp v45, v37, v37 row_half_mirror row_mask:0xf bank_mask:0x5 bound_ctrl:1
	v_add_f32_dpp v42, v38, v38 row_half_mirror row_mask:0xf bank_mask:0xa bound_ctrl:1
	v_add_f32_dpp v43, v39, v39 row_half_mirror row_mask:0xf bank_mask:0xa bound_ctrl:1
	v_add_f32_dpp v44, v40, v40 row_half_mirror row_mask:0xf bank_mask:0xa bound_ctrl:1
	v_add_f32_dpp v45, v41, v41 row_half_mirror row_mask:0xf bank_mask:0xa bound_ctrl:1
	v_cndmask_b32_e64 v80, v44, v42, s[42:43]
	v_cndmask_b32_e64 v121, v42, v44, s[42:43]
	v_cndmask_b32_e64 v82, v45, v43, s[42:43]
	v_cndmask_b32_e64 v122, v43, v45, s[42:43]
	s_nop 0
	s_nop 0
	v_add_f32_dpp v13, v121, v80 quad_perm:[2,3,0,1] row_mask:0xf bank_mask:0xf bound_ctrl:1
	v_add_f32_dpp v14, v122, v82 quad_perm:[2,3,0,1] row_mask:0xf bank_mask:0xf bound_ctrl:1
	v_cndmask_b32_e64 v12, v13, v14, s[44:45]
	v_cndmask_b32_e64 v13, v14, v13, s[44:45]
	v_lshl_add_u32 v16, v100, 11, v99
	v_add_u32_e32 v100, v132, v100
	v_add_f32_dpp v13, v12, v13 quad_perm:[1,0,3,2] row_mask:0xf bank_mask:0xf bound_ctrl:1
	s_cmp_eq_u32 s10, 15
	s_cbranch_scc0 .Lscan_tail_nox
	v_mov_b32_e32 v100, v101
